# v20guard
# speedup vs baseline: 1.0001x; 1.0001x over previous
.LBB0_599:
	s_and_b64 vcc, exec, s[76:77]
	s_cbranch_vccz .LBB0_606
	v_mov_b32_e32 v1, v208
	s_mov_b32 s6, s2
	s_waitcnt vmcnt(1)
	v_ashrrev_i32_e32 v2, 6, v1
	s_waitcnt vmcnt(0)
	v_lshl_add_u32 v18, s6, 3, v2
	s_mov_b32 s6, 0x10800
	v_cmp_gt_i32_e32 vcc, s6, v18
	s_and_saveexec_b64 s[6:7], vcc
	s_cbranch_execz .LBB0_605
	v_and_b32_e32 v2, 63, v1
	v_and_b32_e32 v1, 64, v214
	v_add_u32_e32 v3, 64, v1
	v_xor_b32_e32 v1, 32, v214
	v_cmp_lt_i32_e32 vcc, v1, v3
	v_xor_b32_e32 v4, 16, v214
	s_waitcnt lgkmcnt(0)
	s_load_dwordx4 s[8:11], s[0:1], 0xb8
	v_cndmask_b32_e32 v1, v214, v1, vcc
	v_cmp_lt_i32_e32 vcc, v4, v3
	v_mov_b32_e32 v5, v0
	v_or_b32_e32 v6, 64, v2
	v_cndmask_b32_e32 v4, v214, v4, vcc
	v_lshlrev_b32_e32 v40, 2, v4
	v_xor_b32_e32 v4, 8, v214
	v_cmp_lt_i32_e32 vcc, v4, v3
	v_or_b32_e32 v8, 0x80, v2
	v_or_b32_e32 v10, 0xc0, v2
	v_cndmask_b32_e32 v4, v214, v4, vcc
	v_lshlrev_b32_e32 v41, 2, v4
	v_xor_b32_e32 v4, 4, v214
	v_cmp_lt_i32_e32 vcc, v4, v3
	v_lshlrev_b32_e32 v1, 2, v1
	v_lshlrev_b32_e32 v24, 4, v2
	v_cndmask_b32_e32 v4, v214, v4, vcc
	v_lshlrev_b32_e32 v42, 2, v4
	v_xor_b32_e32 v4, 2, v214
	v_cmp_lt_i32_e32 vcc, v4, v3
	v_lshlrev_b32_e32 v26, 4, v6
	v_lshlrev_b32_e32 v28, 4, v8
	v_cndmask_b32_e32 v4, v214, v4, vcc
	v_lshlrev_b32_e32 v43, 2, v4
	v_xor_b32_e32 v4, 1, v214
	v_cmp_lt_i32_e32 vcc, v4, v3
	v_lshlrev_b32_e32 v30, 4, v10
	s_nop 0
	v_cndmask_b32_e32 v3, v214, v4, vcc
	v_lshlrev_b32_e32 v4, 4, v2
	v_lshlrev_b32_e32 v44, 2, v3
	s_waitcnt lgkmcnt(0)
	v_lshl_add_u64 v[20:21], s[8:9], 0, v[4:5]
	v_lshl_add_u64 v[22:23], s[10:11], 0, v[4:5]
	s_mov_b64 s[8:9], 0
	s_cmp_lg_u32 s25, 0x100
	s_cbranch_scc1 .LBB0_603
	global_load_dwordx4 v[72:75], v[20:21], off
	global_load_dwordx4 v[76:79], v[20:21], off offset:1024
	global_load_dwordx4 v[80:83], v[20:21], off offset:2048
	global_load_dwordx4 v[84:87], v[20:21], off offset:3072
	v_ashrrev_i32_e32 v19, 31, v18
	v_lshlrev_b64 v[120:121], 12, v[18:19]
	v_lshl_add_u64 v[120:121], v[22:23], 0, v[120:121]
	global_load_dwordx4 v[88:91], v[120:121], off
	global_load_dwordx4 v[92:95], v[120:121], off offset:1024
	global_load_dwordx4 v[96:99], v[120:121], off offset:2048
	global_load_dwordx4 v[100:103], v[120:121], off offset:3072
	s_mov_b64 s[12:13], 0x800000
	s_movk_i32 s16, 16
	s_waitcnt vmcnt(0)

.LBB0_610:
	s_or_b64 exec, exec, s[6:7]
	v_ashrrev_i32_e32 v3, 6, v4
	v_and_b32_e32 v2, 63, v4
	v_lshl_add_u32 v4, s52, 3, v3
	s_mov_b32 s6, 0x18800
	v_cmp_gt_i32_e32 vcc, s6, v4
	s_and_saveexec_b64 s[6:7], vcc
	s_cbranch_execz .LBB0_621
	s_load_dwordx2 s[16:17], s[0:1], 0x38
	s_waitcnt lgkmcnt(0)
	s_add_u32 s10, s8, 0x2b27800
	s_addc_u32 s11, s9, 0
	s_add_u32 s12, s8, 0x1b727800
	s_waitcnt vmcnt(0)
	v_lshlrev_b32_e32 v6, 4, v2
	v_mov_b32_e32 v7, v0
	s_addc_u32 s13, s9, 0
	v_lshl_add_u64 v[6:7], s[16:17], 0, v[6:7]
	s_mov_b64 s[16:17], 0
	s_cmp_lg_u32 s25, 0x100
	s_cbranch_scc1 .LBB0_614
	v_readfirstlane_b32 s16, v4
	s_load_dwordx4 s[20:23], s[0:1], 0x0
	s_load_dwordx2 s[68:69], s[0:1], 0x10
	v_lshlrev_b32_e32 v72, 4, v2
	v_mov_b32_e32 v73, v0
	v_lshlrev_b32_e32 v74, 3, v2
	v_mov_b32_e32 v75, v0
	global_load_dwordx4 v[76:79], v[6:7], off
	global_load_dwordx4 v[80:83], v[6:7], off offset:1024
	global_load_dwordx4 v[84:87], v[6:7], off offset:2048
	global_load_dwordx4 v[88:91], v[6:7], off offset:3072
	v_xor_b32_e32 v160, 32, v214
	v_lshlrev_b32_e32 v160, 2, v160
	v_xor_b32_e32 v161, 16, v214
	v_lshlrev_b32_e32 v161, 2, v161
	v_xor_b32_e32 v162, 8, v214
	v_lshlrev_b32_e32 v162, 2, v162
	v_xor_b32_e32 v163, 4, v214
	v_lshlrev_b32_e32 v163, 2, v163
	v_xor_b32_e32 v164, 2, v214
	v_lshlrev_b32_e32 v164, 2, v164
	v_xor_b32_e32 v165, 1, v214
	v_lshlrev_b32_e32 v165, 2, v165
	s_waitcnt lgkmcnt(0)
	s_lshl_b32 s17, s16, 12
	s_add_u32 s20, s20, s17
	s_addc_u32 s21, s21, 0
	s_add_u32 s22, s22, s17
	s_addc_u32 s23, s23, 0
	s_add_u32 s68, s68, s17
	s_addc_u32 s69, s69, 0
	s_lshl_b32 s17, s16, 11
	s_add_u32 s10, s10, s17
	s_addc_u32 s11, s11, 0
	s_lshr_b32 s17, s16, 10
	s_mulk_i32 s17, 0x440
	s_and_b32 s16, s16, 0x3ff
	s_add_u32 s17, s17, s16
	s_add_u32 s17, s17, 0x10000
	s_lshl_b32 s17, s17, 11
	s_add_u32 s12, s12, s17
	s_addc_u32 s13, s13, 0
	v_lshl_add_u64 v[124:125], s[20:21], 0, v[72:73]
	v_lshl_add_u64 v[132:133], s[22:23], 0, v[72:73]
	v_lshl_add_u64 v[166:167], s[68:69], 0, v[72:73]
	v_lshl_add_u64 v[128:129], s[10:11], 0, v[74:75]
	v_lshl_add_u64 v[168:169], s[12:13], 0, v[74:75]
	global_load_dwordx4 v[92:95], v[124:125], off
	global_load_dwordx4 v[96:99], v[124:125], off offset:1024
	global_load_dwordx4 v[100:103], v[124:125], off offset:2048
	global_load_dwordx4 v[104:107], v[124:125], off offset:3072
	s_mov_b64 s[20:21], 0x800000
	s_mov_b64 s[22:23], 0x400000
	s_mov_b64 s[68:69], 0x440000
	s_movk_i32 s16, 16
	s_waitcnt vmcnt(0)

.LBB0_628:
	s_cmpk_gt_i32 s52, 0x73f
	s_mov_b64 s[6:7], -1
	s_cbranch_scc0 .LBB0_658
	s_cmpk_gt_u32 s52, 0xa3f
	s_cbranch_scc0 .LBB0_655
	s_cmpk_gt_u32 s52, 0xe3f
	s_cbranch_scc0 .LBB0_636
	s_cmpk_gt_u32 s52, 0x123f
	s_cbranch_scc0 .LBB0_633
	s_load_dwordx2 s[6:7], s[0:1], 0x18
	v_and_b32_e32 v72, 63, v208
	v_lshrrev_b32_e32 v73, 6, v208
	v_lshl_add_u32 v74, v73, 10, v72
	v_lshlrev_b32_e32 v74, 2, v74
	v_add_u32_e32 v75, 0x8000, v74
	v_add_u32_e32 v76, 0x10000, v74
	v_add_u32_e32 v77, 0x18000, v74
	v_add_u32_e32 v78, 0x20000, v74
	v_add_u32_e32 v79, 0x28000, v74
	v_add_u32_e32 v80, 0x30000, v74
	v_add_u32_e32 v81, 0x38000, v74
	v_mul_u32_u24_e32 v82, 65, v73
	v_add_lshl_u32 v82, v82, v72, 2
	v_lshrrev_b32_e32 v83, 3, v208
	v_and_b32_e32 v84, 7, v208
	v_lshlrev_b32_e32 v84, 3, v84
	v_mul_u32_u24_e32 v85, 0x104, v84
	v_lshl_add_u32 v85, v83, 2, v85
	v_mul_u32_u24_e32 v86, 0x440, v83
	v_add_lshl_u32 v86, v86, v84, 1
	v_add_u32_e32 v87, 0x4200, v82
	v_add_u32_e32 v88, 0x4200, v85
	v_add_u32_e32 v89, 0x410, v85
	v_add_u32_e32 v90, 0x410, v88
	s_lshl_b32 s65, s25, 2
	s_mov_b32 s20, 0
	s_waitcnt lgkmcnt(0)
	s_mov_b32 s21, s52
	s_add_i32 s22, s21, 0xffffedc0
	s_lshr_b32 s23, s22, 8
	s_lshl_b32 s23, s23, 22
	s_and_b32 s56, s22, 15
	s_lshl_b32 s56, s56, 18
	s_add_u32 s23, s23, s56
	s_lshr_b32 s56, s22, 4
	s_and_b32 s56, s56, 15
	s_lshl_b32 s56, s56, 8
	s_add_u32 s23, s23, s56
	s_add_u32 s10, s6, s23
	s_addc_u32 s11, s7, 0
	global_load_dword v108, v74, s[10:11]
	global_load_dword v109, v75, s[10:11]
	global_load_dword v110, v76, s[10:11]
	global_load_dword v111, v77, s[10:11]
	global_load_dword v112, v78, s[10:11]
	global_load_dword v113, v79, s[10:11]
	global_load_dword v114, v80, s[10:11]
	global_load_dword v115, v81, s[10:11]
	s_add_i32 s21, s21, s25
	s_add_i32 s22, s21, 0xffffedc0
	s_lshr_b32 s23, s22, 8
	s_lshl_b32 s23, s23, 22
	s_and_b32 s56, s22, 15
	s_lshl_b32 s56, s56, 18
	s_add_u32 s23, s23, s56
	s_lshr_b32 s56, s22, 4
	s_and_b32 s56, s56, 15
	s_lshl_b32 s56, s56, 8
	s_add_u32 s23, s23, s56
	s_add_u32 s10, s6, s23
	s_addc_u32 s11, s7, 0
	global_load_dword v116, v74, s[10:11]
	global_load_dword v117, v75, s[10:11]
	global_load_dword v118, v76, s[10:11]
	global_load_dword v119, v77, s[10:11]
	global_load_dword v120, v78, s[10:11]
	global_load_dword v121, v79, s[10:11]
	global_load_dword v122, v80, s[10:11]
	global_load_dword v123, v81, s[10:11]
	s_add_i32 s21, s21, s25
	s_add_i32 s22, s21, 0xffffedc0
	s_lshr_b32 s23, s22, 8
	s_lshl_b32 s23, s23, 22
	s_and_b32 s56, s22, 15
	s_lshl_b32 s56, s56, 18
	s_add_u32 s23, s23, s56
	s_lshr_b32 s56, s22, 4
	s_and_b32 s56, s56, 15
	s_lshl_b32 s56, s56, 8
	s_add_u32 s23, s23, s56
	s_add_u32 s10, s6, s23
	s_addc_u32 s11, s7, 0
	global_load_dword v124, v74, s[10:11]
	global_load_dword v125, v75, s[10:11]
	global_load_dword v126, v76, s[10:11]
	global_load_dword v127, v77, s[10:11]
	global_load_dword v128, v78, s[10:11]
	global_load_dword v129, v79, s[10:11]
	global_load_dword v130, v80, s[10:11]
	global_load_dword v131, v81, s[10:11]
	s_add_i32 s21, s21, s25
	s_add_i32 s22, s21, 0xffffedc0
	s_lshr_b32 s23, s22, 8
	s_lshl_b32 s23, s23, 22
	s_and_b32 s56, s22, 15
	s_lshl_b32 s56, s56, 18
	s_add_u32 s23, s23, s56
	s_lshr_b32 s56, s22, 4
	s_and_b32 s56, s56, 15
	s_lshl_b32 s56, s56, 8
	s_add_u32 s23, s23, s56
	s_add_u32 s10, s6, s23
	s_addc_u32 s11, s7, 0
	global_load_dword v132, v74, s[10:11]
	global_load_dword v133, v75, s[10:11]
	global_load_dword v134, v76, s[10:11]
	global_load_dword v135, v77, s[10:11]
	global_load_dword v136, v78, s[10:11]
	global_load_dword v137, v79, s[10:11]
	global_load_dword v138, v80, s[10:11]
	global_load_dword v139, v81, s[10:11]
	s_add_i32 s21, s21, s25
	s_add_i32 s22, s52, 0xffffedc0
	s_lshr_b32 s23, s22, 4
	s_mul_i32 s23, s23, 0x22000
	s_and_b32 s56, s22, 15
	s_lshl_b32 s56, s56, 7
	s_add_u32 s23, s23, s56
	s_add_u32 s12, s16, s23
	s_addc_u32 s13, s17, 0
.Lp0v_loop:
	s_cmp_eq_u32 s20, 0
	s_cbranch_scc1 .Lp0v_cnt0
	s_waitcnt vmcnt(0)
	s_branch .Lp0v_go0
.Lp0v_cnt0:
	s_waitcnt vmcnt(24)
.Lp0v_go0:
	ds_write_b32 v82, v108
	ds_write_b32 v82, v109 offset:2080
	ds_write_b32 v82, v110 offset:4160
	ds_write_b32 v82, v111 offset:6240
	ds_write_b32 v82, v112 offset:8320
	ds_write_b32 v82, v113 offset:10400
	ds_write_b32 v82, v114 offset:12480
	ds_write_b32 v82, v115 offset:14560
	s_waitcnt lgkmcnt(0)
	s_add_i32 s21, s52, s65
	s_cmpk_gt_i32 s21, 0x323f
	s_cbranch_scc1 .Lp0v_nonext0
	s_add_i32 s22, s21, 0xffffedc0
	s_lshr_b32 s23, s22, 8
	s_lshl_b32 s23, s23, 22
	s_and_b32 s56, s22, 15
	s_lshl_b32 s56, s56, 18
	s_add_u32 s23, s23, s56
	s_lshr_b32 s56, s22, 4
	s_and_b32 s56, s56, 15
	s_lshl_b32 s56, s56, 8
	s_add_u32 s23, s23, s56
	s_add_u32 s10, s6, s23
	s_addc_u32 s11, s7, 0
	global_load_dword v108, v74, s[10:11]
	global_load_dword v109, v75, s[10:11]
	global_load_dword v110, v76, s[10:11]
	global_load_dword v111, v77, s[10:11]
	global_load_dword v112, v78, s[10:11]
	global_load_dword v113, v79, s[10:11]
	global_load_dword v114, v80, s[10:11]
	global_load_dword v115, v81, s[10:11]
	s_branch .Lp0v_bar0
.Lp0v_nonext0:
	s_mov_b32 s20, 1
.Lp0v_bar0:
	s_barrier
	ds_read2_b32 v[96:97], v85 offset1:65
	ds_read2_b32 v[98:99], v85 offset0:130 offset1:195
	ds_read2_b32 v[100:101], v89 offset1:65
	ds_read2_b32 v[102:103], v89 offset0:130 offset1:195
	s_waitcnt lgkmcnt(0)
	v_cvt_pk_bf16_f32 v104, v96, v97
	v_cvt_pk_bf16_f32 v105, v98, v99
	v_cvt_pk_bf16_f32 v106, v100, v101
	v_cvt_pk_bf16_f32 v107, v102, v103
	global_store_dwordx4 v86, v[104:107], s[12:13]
	s_add_i32 s52, s52, s25
	s_add_i32 s22, s52, 0xffffedc0
	s_lshr_b32 s23, s22, 4
	s_mul_i32 s23, s23, 0x22000
	s_and_b32 s56, s22, 15
	s_lshl_b32 s56, s56, 7
	s_add_u32 s23, s23, s56
	s_add_u32 s12, s16, s23
	s_addc_u32 s13, s17, 0
	s_cmpk_gt_i32 s52, 0x323f
	s_cbranch_scc1 .Lp0v_done
	s_cmp_eq_u32 s20, 0
	s_cbranch_scc1 .Lp0v_cnt1
	s_waitcnt vmcnt(0)
	s_branch .Lp0v_go1

.Lp0v_go1:
	ds_write_b32 v87, v116
	ds_write_b32 v87, v117 offset:2080
	ds_write_b32 v87, v118 offset:4160
	ds_write_b32 v87, v119 offset:6240
	ds_write_b32 v87, v120 offset:8320
	ds_write_b32 v87, v121 offset:10400
	ds_write_b32 v87, v122 offset:12480
	ds_write_b32 v87, v123 offset:14560
	s_waitcnt lgkmcnt(0)
	s_add_i32 s21, s52, s65
	s_cmpk_gt_i32 s21, 0x323f
	s_cbranch_scc1 .Lp0v_nonext1
	s_add_i32 s22, s21, 0xffffedc0
	s_lshr_b32 s23, s22, 8
	s_lshl_b32 s23, s23, 22
	s_and_b32 s56, s22, 15
	s_lshl_b32 s56, s56, 18
	s_add_u32 s23, s23, s56
	s_lshr_b32 s56, s22, 4
	s_and_b32 s56, s56, 15
	s_lshl_b32 s56, s56, 8
	s_add_u32 s23, s23, s56
	s_add_u32 s10, s6, s23
	s_addc_u32 s11, s7, 0
	global_load_dword v116, v74, s[10:11]
	global_load_dword v117, v75, s[10:11]
	global_load_dword v118, v76, s[10:11]
	global_load_dword v119, v77, s[10:11]
	global_load_dword v120, v78, s[10:11]
	global_load_dword v121, v79, s[10:11]
	global_load_dword v122, v80, s[10:11]
	global_load_dword v123, v81, s[10:11]
	s_branch .Lp0v_bar1

.Lp0v_bar1:
	s_barrier
	ds_read2_b32 v[96:97], v88 offset1:65
	ds_read2_b32 v[98:99], v88 offset0:130 offset1:195
	ds_read2_b32 v[100:101], v90 offset1:65
	ds_read2_b32 v[102:103], v90 offset0:130 offset1:195
	s_waitcnt lgkmcnt(0)
	v_cvt_pk_bf16_f32 v104, v96, v97
	v_cvt_pk_bf16_f32 v105, v98, v99
	v_cvt_pk_bf16_f32 v106, v100, v101
	v_cvt_pk_bf16_f32 v107, v102, v103
	global_store_dwordx4 v86, v[104:107], s[12:13]
	s_add_i32 s52, s52, s25
	s_add_i32 s22, s52, 0xffffedc0
	s_lshr_b32 s23, s22, 4
	s_mul_i32 s23, s23, 0x22000
	s_and_b32 s56, s22, 15
	s_lshl_b32 s56, s56, 7
	s_add_u32 s23, s23, s56
	s_add_u32 s12, s16, s23
	s_addc_u32 s13, s17, 0
	s_cmpk_gt_i32 s52, 0x323f
	s_cbranch_scc1 .Lp0v_done
	s_cmp_eq_u32 s20, 0
	s_cbranch_scc1 .Lp0v_cnt2
	s_waitcnt vmcnt(0)
	s_branch .Lp0v_go2

.Lp0v_go2:
	ds_write_b32 v82, v124
	ds_write_b32 v82, v125 offset:2080
	ds_write_b32 v82, v126 offset:4160
	ds_write_b32 v82, v127 offset:6240
	ds_write_b32 v82, v128 offset:8320
	ds_write_b32 v82, v129 offset:10400
	ds_write_b32 v82, v130 offset:12480
	ds_write_b32 v82, v131 offset:14560
	s_waitcnt lgkmcnt(0)
	s_add_i32 s21, s52, s65
	s_cmpk_gt_i32 s21, 0x323f
	s_cbranch_scc1 .Lp0v_nonext2
	s_add_i32 s22, s21, 0xffffedc0
	s_lshr_b32 s23, s22, 8
	s_lshl_b32 s23, s23, 22
	s_and_b32 s56, s22, 15
	s_lshl_b32 s56, s56, 18
	s_add_u32 s23, s23, s56
	s_lshr_b32 s56, s22, 4
	s_and_b32 s56, s56, 15
	s_lshl_b32 s56, s56, 8
	s_add_u32 s23, s23, s56
	s_add_u32 s10, s6, s23
	s_addc_u32 s11, s7, 0
	global_load_dword v124, v74, s[10:11]
	global_load_dword v125, v75, s[10:11]
	global_load_dword v126, v76, s[10:11]
	global_load_dword v127, v77, s[10:11]
	global_load_dword v128, v78, s[10:11]
	global_load_dword v129, v79, s[10:11]
	global_load_dword v130, v80, s[10:11]
	global_load_dword v131, v81, s[10:11]
	s_branch .Lp0v_bar2

.Lp0v_go3:
	ds_write_b32 v87, v132
	ds_write_b32 v87, v133 offset:2080
	ds_write_b32 v87, v134 offset:4160
	ds_write_b32 v87, v135 offset:6240
	ds_write_b32 v87, v136 offset:8320
	ds_write_b32 v87, v137 offset:10400
	ds_write_b32 v87, v138 offset:12480
	ds_write_b32 v87, v139 offset:14560
	s_waitcnt lgkmcnt(0)
	s_add_i32 s21, s52, s65
	s_cmpk_gt_i32 s21, 0x323f
	s_cbranch_scc1 .Lp0v_nonext3
	s_add_i32 s22, s21, 0xffffedc0
	s_lshr_b32 s23, s22, 8
	s_lshl_b32 s23, s23, 22
	s_and_b32 s56, s22, 15
	s_lshl_b32 s56, s56, 18
	s_add_u32 s23, s23, s56
	s_lshr_b32 s56, s22, 4
	s_and_b32 s56, s56, 15
	s_lshl_b32 s56, s56, 8
	s_add_u32 s23, s23, s56
	s_add_u32 s10, s6, s23
	s_addc_u32 s11, s7, 0
	global_load_dword v132, v74, s[10:11]
	global_load_dword v133, v75, s[10:11]
	global_load_dword v134, v76, s[10:11]
	global_load_dword v135, v77, s[10:11]
	global_load_dword v136, v78, s[10:11]
	global_load_dword v137, v79, s[10:11]
	global_load_dword v138, v80, s[10:11]
	global_load_dword v139, v81, s[10:11]
	s_branch .Lp0v_bar3

.Lp0v_bar3:
	s_barrier
	ds_read2_b32 v[96:97], v88 offset1:65
	ds_read2_b32 v[98:99], v88 offset0:130 offset1:195
	ds_read2_b32 v[100:101], v90 offset1:65
	ds_read2_b32 v[102:103], v90 offset0:130 offset1:195
	s_waitcnt lgkmcnt(0)
	v_cvt_pk_bf16_f32 v104, v96, v97
	v_cvt_pk_bf16_f32 v105, v98, v99
	v_cvt_pk_bf16_f32 v106, v100, v101
	v_cvt_pk_bf16_f32 v107, v102, v103
	global_store_dwordx4 v86, v[104:107], s[12:13]
	s_add_i32 s52, s52, s25
	s_add_i32 s22, s52, 0xffffedc0
	s_lshr_b32 s23, s22, 4
	s_mul_i32 s23, s23, 0x22000
	s_and_b32 s56, s22, 15
	s_lshl_b32 s56, s56, 7
	s_add_u32 s23, s23, s56
	s_add_u32 s12, s16, s23
	s_addc_u32 s13, s17, 0
	s_cmpk_gt_i32 s52, 0x323f
	s_cbranch_scc1 .Lp0v_done
	s_branch .Lp0v_loop
.Lp0v_done:
	s_branch .LBB0_681
